# attention epilogue: v_permlane32_swap pairs, 8 dwordx4 MIX stores instead of 16 dwordx2 (same bytes and addresses)
# baseline (speedup 1.0000x reference)
.LBB0_736:
	s_andn2_b64 vcc, exec, s[8:9]
	s_waitcnt lgkmcnt(0)
	s_barrier
	s_cbranch_vccnz .LBB0_738
	global_load_dwordx4 v[112:115], v[136:137], off
	global_load_dwordx4 v[108:111], v[136:137], off offset:32
	global_load_dwordx4 v[104:107], v[136:137], off offset:64
	global_load_dwordx4 v[100:103], v[136:137], off offset:96
	global_load_dwordx4 v[96:99], v[136:137], off offset:128
	global_load_dwordx4 v[92:95], v[136:137], off offset:160
	global_load_dwordx4 v[88:91], v[136:137], off offset:192
	global_load_dwordx4 v[84:87], v[136:137], off offset:224
	global_load_dwordx4 v[80:83], v[136:137], off offset:256
	global_load_dwordx4 v[76:79], v[136:137], off offset:288
	global_load_dwordx4 v[72:75], v[136:137], off offset:320
	global_load_dwordx4 v[68:71], v[136:137], off offset:352
	ds_read2st64_b32 v[126:127], v157 offset1:1
	ds_read2st64_b32 v[128:129], v157 offset0:2 offset1:3
	ds_read2st64_b32 v[130:131], v157 offset0:4 offset1:5
	ds_read2st64_b32 v[138:139], v157 offset0:6 offset1:7
	ds_read2st64_b32 v[142:143], v157 offset0:8 offset1:9
	ds_read2st64_b32 v[144:145], v157 offset0:10 offset1:11
	ds_read2st64_b32 v[146:147], v157 offset0:12 offset1:13
	ds_read2st64_b32 v[176:177], v157 offset0:14 offset1:15
	ds_read2st64_b32 v[178:179], v157 offset0:16 offset1:17
	ds_read2st64_b32 v[180:181], v157 offset0:18 offset1:19
	ds_read2st64_b32 v[182:183], v157 offset0:20 offset1:21
	ds_read2st64_b32 v[184:185], v157 offset0:22 offset1:23
	ds_read2st64_b32 v[186:187], v157 offset0:24 offset1:25
	ds_read2st64_b32 v[188:189], v157 offset0:26 offset1:27
	ds_read2st64_b32 v[190:191], v157 offset0:28 offset1:29
	ds_read2st64_b32 v[192:193], v157 offset0:30 offset1:31
	ds_read2st64_b32 v[194:195], v157 offset0:32 offset1:33
	ds_read2st64_b32 v[196:197], v157 offset0:34 offset1:35
	ds_read2st64_b32 v[198:199], v157 offset0:36 offset1:37
	ds_read2st64_b32 v[200:201], v157 offset0:38 offset1:39
	ds_read2st64_b32 v[202:203], v157 offset0:40 offset1:41
	ds_read2st64_b32 v[204:205], v157 offset0:42 offset1:43
	ds_read2st64_b32 v[206:207], v157 offset0:44 offset1:45
	ds_read2st64_b32 v[208:209], v157 offset0:46 offset1:47
	ds_read2st64_b32 v[118:119], v157 offset0:58 offset1:59
	ds_read2st64_b32 v[210:211], v157 offset0:48 offset1:49
	ds_read2st64_b32 v[212:213], v157 offset0:50 offset1:51
	ds_read2st64_b32 v[214:215], v157 offset0:52 offset1:53
	ds_read2st64_b32 v[216:217], v157 offset0:54 offset1:55
	ds_read2st64_b32 v[122:123], v157 offset0:60 offset1:61
	ds_read2st64_b32 v[218:219], v157 offset0:56 offset1:57
	ds_read2st64_b32 v[124:125], v157 offset0:62 offset1:63
	s_waitcnt lgkmcnt(7)
	v_pk_fma_f32 v[118:119], v[14:15], v[116:117], v[118:119] op_sel_hi:[1,0,1] neg_lo:[0,0,1] neg_hi:[0,0,1]
	v_pk_fma_f32 v[64:65], v[64:65], v[116:117], v[146:147] op_sel_hi:[1,0,1] neg_lo:[0,0,1] neg_hi:[0,0,1]
	s_waitcnt lgkmcnt(2)
	v_pk_fma_f32 v[14:15], v[16:17], v[116:117], v[122:123] op_sel_hi:[1,0,1] neg_lo:[0,0,1] neg_hi:[0,0,1]
	v_pk_mul_f32 v[146:147], v[64:65], v[64:65]
	s_waitcnt lgkmcnt(0)
	v_pk_fma_f32 v[16:17], v[18:19], v[116:117], v[124:125] op_sel_hi:[1,0,1] neg_lo:[0,0,1] neg_hi:[0,0,1]
	v_pk_fma_f32 v[18:19], v[54:55], v[116:117], v[128:129] op_sel_hi:[1,0,1] neg_lo:[0,0,1] neg_hi:[0,0,1]
	v_pk_fma_f32 v[54:55], v[52:53], v[116:117], v[126:127] op_sel_hi:[1,0,1] neg_lo:[0,0,1] neg_hi:[0,0,1]
	v_pk_mul_f32 v[128:129], v[18:19], v[18:19]
	v_pk_mul_f32 v[126:127], v[54:55], v[54:55]
	v_pk_fma_f32 v[52:53], v[58:59], v[116:117], v[138:139] op_sel_hi:[1,0,1] neg_lo:[0,0,1] neg_hi:[0,0,1]
	v_add_f32_e32 v126, v126, v127
	v_pk_fma_f32 v[58:59], v[56:57], v[116:117], v[130:131] op_sel_hi:[1,0,1] neg_lo:[0,0,1] neg_hi:[0,0,1]
	v_add_f32_e32 v126, v126, v128
	v_pk_mul_f32 v[130:131], v[58:59], v[58:59]
	v_add_f32_e32 v126, v126, v129
	v_add_f32_e32 v126, v126, v130
	v_pk_mul_f32 v[138:139], v[52:53], v[52:53]
	v_add_f32_e32 v126, v126, v131
	v_pk_fma_f32 v[56:57], v[62:63], v[116:117], v[144:145] op_sel_hi:[1,0,1] neg_lo:[0,0,1] neg_hi:[0,0,1]
	v_pk_fma_f32 v[62:63], v[60:61], v[116:117], v[142:143] op_sel_hi:[1,0,1] neg_lo:[0,0,1] neg_hi:[0,0,1]
	v_add_f32_e32 v126, v126, v138
	v_pk_mul_f32 v[142:143], v[62:63], v[62:63]
	v_add_f32_e32 v126, v126, v139
	v_add_f32_e32 v126, v126, v142
	v_pk_mul_f32 v[144:145], v[56:57], v[56:57]
	v_add_f32_e32 v126, v126, v143
	v_add_f32_e32 v126, v126, v144
	v_add_f32_e32 v126, v126, v145
	v_pk_fma_f32 v[60:61], v[66:67], v[116:117], v[176:177] op_sel_hi:[1,0,1] neg_lo:[0,0,1] neg_hi:[0,0,1]
	v_add_f32_e32 v126, v126, v146
	v_pk_mul_f32 v[176:177], v[60:61], v[60:61]
	v_add_f32_e32 v126, v126, v147
	v_pk_fma_f32 v[66:67], v[36:37], v[116:117], v[178:179] op_sel_hi:[1,0,1] neg_lo:[0,0,1] neg_hi:[0,0,1]
	v_add_f32_e32 v126, v126, v176
	v_pk_mul_f32 v[178:179], v[66:67], v[66:67]
	v_add_f32_e32 v126, v126, v177
	v_pk_fma_f32 v[38:39], v[38:39], v[116:117], v[180:181] op_sel_hi:[1,0,1] neg_lo:[0,0,1] neg_hi:[0,0,1]
	v_add_f32_e32 v126, v126, v178
	v_pk_mul_f32 v[180:181], v[38:39], v[38:39]
	v_add_f32_e32 v126, v126, v179
	v_pk_fma_f32 v[36:37], v[42:43], v[116:117], v[184:185] op_sel_hi:[1,0,1] neg_lo:[0,0,1] neg_hi:[0,0,1]
	v_pk_fma_f32 v[42:43], v[40:41], v[116:117], v[182:183] op_sel_hi:[1,0,1] neg_lo:[0,0,1] neg_hi:[0,0,1]
	v_add_f32_e32 v126, v126, v180
	v_pk_mul_f32 v[182:183], v[42:43], v[42:43]
	v_add_f32_e32 v126, v126, v181
	v_add_f32_e32 v126, v126, v182
	v_pk_mul_f32 v[184:185], v[36:37], v[36:37]
	v_add_f32_e32 v126, v126, v183
	v_pk_fma_f32 v[40:41], v[46:47], v[116:117], v[188:189] op_sel_hi:[1,0,1] neg_lo:[0,0,1] neg_hi:[0,0,1]
	v_pk_fma_f32 v[46:47], v[44:45], v[116:117], v[186:187] op_sel_hi:[1,0,1] neg_lo:[0,0,1] neg_hi:[0,0,1]
	v_add_f32_e32 v126, v126, v184
	v_pk_mul_f32 v[186:187], v[46:47], v[46:47]
	v_add_f32_e32 v126, v126, v185
	v_add_f32_e32 v126, v126, v186
	v_pk_mul_f32 v[188:189], v[40:41], v[40:41]
	v_add_f32_e32 v126, v126, v187
	v_pk_fma_f32 v[48:49], v[48:49], v[116:117], v[190:191] op_sel_hi:[1,0,1] neg_lo:[0,0,1] neg_hi:[0,0,1]
	v_add_f32_e32 v126, v126, v188
	v_pk_mul_f32 v[190:191], v[48:49], v[48:49]
	v_add_f32_e32 v126, v126, v189
	v_pk_fma_f32 v[44:45], v[50:51], v[116:117], v[192:193] op_sel_hi:[1,0,1] neg_lo:[0,0,1] neg_hi:[0,0,1]
	v_add_f32_e32 v126, v126, v190
	v_pk_mul_f32 v[192:193], v[44:45], v[44:45]
	v_add_f32_e32 v126, v126, v191
	v_pk_fma_f32 v[50:51], v[20:21], v[116:117], v[194:195] op_sel_hi:[1,0,1] neg_lo:[0,0,1] neg_hi:[0,0,1]
	v_add_f32_e32 v126, v126, v192
	v_pk_mul_f32 v[194:195], v[50:51], v[50:51]
	v_add_f32_e32 v126, v126, v193
	v_pk_fma_f32 v[22:23], v[22:23], v[116:117], v[196:197] op_sel_hi:[1,0,1] neg_lo:[0,0,1] neg_hi:[0,0,1]
	v_add_f32_e32 v126, v126, v194
	v_pk_mul_f32 v[196:197], v[22:23], v[22:23]
	v_add_f32_e32 v126, v126, v195
	v_pk_fma_f32 v[198:199], v[24:25], v[116:117], v[198:199] op_sel_hi:[1,0,1] neg_lo:[0,0,1] neg_hi:[0,0,1]
	v_add_f32_e32 v126, v126, v196
	v_pk_fma_f32 v[20:21], v[26:27], v[116:117], v[200:201] op_sel_hi:[1,0,1] neg_lo:[0,0,1] neg_hi:[0,0,1]
	v_pk_mul_f32 v[200:201], v[198:199], v[198:199]
	v_add_f32_e32 v126, v126, v197
	v_add_f32_e32 v126, v126, v200
	v_pk_mul_f32 v[26:27], v[20:21], v[20:21]
	v_add_f32_e32 v126, v126, v201
	v_pk_fma_f32 v[202:203], v[28:29], v[116:117], v[202:203] op_sel_hi:[1,0,1] neg_lo:[0,0,1] neg_hi:[0,0,1]
	v_add_f32_e32 v26, v126, v26
	v_pk_mul_f32 v[28:29], v[202:203], v[202:203]
	v_add_f32_e32 v26, v26, v27
	v_pk_fma_f32 v[24:25], v[30:31], v[116:117], v[204:205] op_sel_hi:[1,0,1] neg_lo:[0,0,1] neg_hi:[0,0,1]
	v_add_f32_e32 v26, v26, v28
	v_pk_mul_f32 v[30:31], v[24:25], v[24:25]
	v_add_f32_e32 v26, v26, v29
	v_pk_fma_f32 v[206:207], v[32:33], v[116:117], v[206:207] op_sel_hi:[1,0,1] neg_lo:[0,0,1] neg_hi:[0,0,1]
	v_add_f32_e32 v26, v26, v30
	v_pk_mul_f32 v[32:33], v[206:207], v[206:207]
	v_add_f32_e32 v26, v26, v31
	v_pk_fma_f32 v[34:35], v[34:35], v[116:117], v[208:209] op_sel_hi:[1,0,1] neg_lo:[0,0,1] neg_hi:[0,0,1]
	v_add_f32_e32 v26, v26, v32
	v_pk_mul_f32 v[204:205], v[34:35], v[34:35]
	v_add_f32_e32 v26, v26, v33
	v_pk_fma_f32 v[210:211], v[4:5], v[116:117], v[210:211] op_sel_hi:[1,0,1] neg_lo:[0,0,1] neg_hi:[0,0,1]
	v_add_f32_e32 v26, v26, v204
	v_pk_mul_f32 v[4:5], v[210:211], v[210:211]
	v_add_f32_e32 v26, v26, v205
	v_pk_fma_f32 v[208:209], v[6:7], v[116:117], v[212:213] op_sel_hi:[1,0,1] neg_lo:[0,0,1] neg_hi:[0,0,1]
	v_add_f32_e32 v4, v26, v4
	v_pk_mul_f32 v[6:7], v[208:209], v[208:209]
	v_add_f32_e32 v4, v4, v5
	v_pk_fma_f32 v[214:215], v[8:9], v[116:117], v[214:215] op_sel_hi:[1,0,1] neg_lo:[0,0,1] neg_hi:[0,0,1]
	v_add_f32_e32 v4, v4, v6
	v_pk_mul_f32 v[8:9], v[214:215], v[214:215]
	v_add_f32_e32 v4, v4, v7
	v_pk_fma_f32 v[212:213], v[10:11], v[116:117], v[216:217] op_sel_hi:[1,0,1] neg_lo:[0,0,1] neg_hi:[0,0,1]
	v_add_f32_e32 v4, v4, v8
	v_pk_mul_f32 v[10:11], v[212:213], v[212:213]
	v_add_f32_e32 v4, v4, v9
	v_pk_fma_f32 v[12:13], v[12:13], v[116:117], v[218:219] op_sel_hi:[1,0,1] neg_lo:[0,0,1] neg_hi:[0,0,1]
	v_add_f32_e32 v4, v4, v10
	v_pk_mul_f32 v[116:117], v[12:13], v[12:13]
	v_add_f32_e32 v4, v4, v11
	v_add_f32_e32 v4, v4, v116
	v_pk_mul_f32 v[120:121], v[118:119], v[118:119]
	v_add_f32_e32 v4, v4, v117
	v_add_f32_e32 v4, v4, v120
	v_pk_mul_f32 v[122:123], v[14:15], v[14:15]
	v_add_f32_e32 v4, v4, v121
	v_add_f32_e32 v4, v4, v122
	v_pk_mul_f32 v[124:125], v[16:17], v[16:17]
	v_add_f32_e32 v4, v4, v123
	v_add_f32_e32 v4, v4, v124
	v_add_f32_e32 v116, v4, v125
	global_load_dwordx4 v[4:7], v[136:137], off offset:384
	global_load_dwordx4 v[8:11], v[136:137], off offset:416
	global_load_dwordx4 v[26:29], v[136:137], off offset:448
	global_load_dwordx4 v[30:33], v[136:137], off offset:480
	ds_bpermute_b32 v117, v1, v116
	s_lshl_b32 s6, s48, 1
	s_waitcnt lgkmcnt(0)
	v_add_f32_e32 v116, v116, v117
	v_fmamk_f32 v116, v116, 0x3c000000, v173
	v_mul_f32_e32 v117, 0x4f800000, v116
	v_cmp_gt_f32_e32 vcc, s66, v116
	s_nop 1
	v_cndmask_b32_e32 v120, v116, v117, vcc
	v_sqrt_f32_e32 v121, v120
	v_lshlrev_b64 v[116:117], 11, v[2:3]
	v_lshl_add_u64 v[116:117], s[4:5], 0, v[116:117]
	v_lshl_add_u64 v[116:117], v[116:117], 0, s[6:7]
	v_add_u32_e32 v2, -1, v121
	v_fma_f32 v122, -v2, v121, v120
	v_cmp_ge_f32_e64 s[0:1], 0, v122
	v_add_u32_e32 v122, 1, v121
	s_nop 0
	v_cndmask_b32_e64 v2, v121, v2, s[0:1]
	v_fma_f32 v121, -v122, v121, v120
	v_cmp_lt_f32_e64 s[0:1], 0, v121
	s_nop 1
	v_cndmask_b32_e64 v2, v2, v122, s[0:1]
	v_mul_f32_e32 v121, 0x37800000, v2
	v_cndmask_b32_e32 v2, v2, v121, vcc
	v_cmp_class_f32_e32 vcc, v120, v174
	s_nop 1
	v_cndmask_b32_e32 v120, v2, v120, vcc
	v_div_scale_f32 v121, s[0:1], v120, v120, s67
	v_rcp_f32_e32 v122, v121
	v_lshlrev_b32_e32 v2, 1, v134
	v_lshl_add_u64 v[116:117], v[116:117], 0, v[2:3]
	v_fma_f32 v2, -v121, v122, 1.0
	v_fmac_f32_e32 v122, v2, v122
	v_div_scale_f32 v2, vcc, s67, v120, s67
	v_mul_f32_e32 v123, v2, v122
	v_fma_f32 v124, -v121, v123, v2
	v_fmac_f32_e32 v123, v124, v122
	v_fma_f32 v2, -v121, v123, v2
	v_div_fmas_f32 v2, v2, v122, v123
	v_div_fixup_f32 v2, v2, v120, s67
	s_waitcnt vmcnt(0)
	v_mbcnt_lo_u32_b32 v124, -1, 0
	v_mbcnt_hi_u32_b32 v124, -1, v124
	v_and_b32_e32 v124, 32, v124
	v_lshrrev_b32_e32 v124, 2, v124
	v_mov_b32_e32 v125, 0
	v_lshl_add_u64 v[116:117], v[116:117], 0, v[124:125]
	v_pk_mul_f32 v[120:121], v[54:55], v[2:3] op_sel_hi:[1,0]
	v_pk_mul_f32 v[122:123], v[18:19], v[2:3] op_sel_hi:[1,0]
	v_pk_mul_f32 v[120:121], v[112:113], v[120:121]
	v_pk_mul_f32 v[122:123], v[114:115], v[122:123]
	v_cvt_pk_bf16_f32 v112, v120, v121
	v_cvt_pk_bf16_f32 v113, v122, v123
	v_pk_mul_f32 v[120:121], v[58:59], v[2:3] op_sel_hi:[1,0]
	v_pk_mul_f32 v[122:123], v[52:53], v[2:3] op_sel_hi:[1,0]
	v_pk_mul_f32 v[120:121], v[108:109], v[120:121]
	v_pk_mul_f32 v[122:123], v[110:111], v[122:123]
	v_cvt_pk_bf16_f32 v114, v120, v121
	v_cvt_pk_bf16_f32 v115, v122, v123
	s_nop 1
	v_permlane32_swap_b32 v112, v114
	v_permlane32_swap_b32 v113, v115
	global_store_dwordx4 v[116:117], v[112:115], off
	v_pk_mul_f32 v[120:121], v[62:63], v[2:3] op_sel_hi:[1,0]
	v_pk_mul_f32 v[122:123], v[56:57], v[2:3] op_sel_hi:[1,0]
	v_pk_mul_f32 v[120:121], v[104:105], v[120:121]
	v_pk_mul_f32 v[122:123], v[106:107], v[122:123]
	v_cvt_pk_bf16_f32 v104, v120, v121
	v_cvt_pk_bf16_f32 v105, v122, v123
	v_pk_mul_f32 v[120:121], v[64:65], v[2:3] op_sel_hi:[1,0]
	v_pk_mul_f32 v[122:123], v[60:61], v[2:3] op_sel_hi:[1,0]
	v_pk_mul_f32 v[120:121], v[100:101], v[120:121]
	v_pk_mul_f32 v[122:123], v[102:103], v[122:123]
	v_cvt_pk_bf16_f32 v106, v120, v121
	v_cvt_pk_bf16_f32 v107, v122, v123
	s_nop 1
	v_permlane32_swap_b32 v104, v106
	v_permlane32_swap_b32 v105, v107
	global_store_dwordx4 v[116:117], v[104:107], off offset:32
	v_pk_mul_f32 v[120:121], v[66:67], v[2:3] op_sel_hi:[1,0]
	v_pk_mul_f32 v[122:123], v[38:39], v[2:3] op_sel_hi:[1,0]
	v_pk_mul_f32 v[120:121], v[96:97], v[120:121]
	v_pk_mul_f32 v[122:123], v[98:99], v[122:123]
	v_cvt_pk_bf16_f32 v96, v120, v121
	v_cvt_pk_bf16_f32 v97, v122, v123
	v_pk_mul_f32 v[120:121], v[42:43], v[2:3] op_sel_hi:[1,0]
	v_pk_mul_f32 v[122:123], v[36:37], v[2:3] op_sel_hi:[1,0]
	v_pk_mul_f32 v[120:121], v[92:93], v[120:121]
	v_pk_mul_f32 v[122:123], v[94:95], v[122:123]
	v_cvt_pk_bf16_f32 v98, v120, v121
	v_cvt_pk_bf16_f32 v99, v122, v123
	s_nop 1
	v_permlane32_swap_b32 v96, v98
	v_permlane32_swap_b32 v97, v99
	global_store_dwordx4 v[116:117], v[96:99], off offset:64
	v_pk_mul_f32 v[120:121], v[46:47], v[2:3] op_sel_hi:[1,0]
	v_pk_mul_f32 v[122:123], v[40:41], v[2:3] op_sel_hi:[1,0]
	v_pk_mul_f32 v[120:121], v[88:89], v[120:121]
	v_pk_mul_f32 v[122:123], v[90:91], v[122:123]
	v_cvt_pk_bf16_f32 v88, v120, v121
	v_cvt_pk_bf16_f32 v89, v122, v123
	v_pk_mul_f32 v[120:121], v[48:49], v[2:3] op_sel_hi:[1,0]
	v_pk_mul_f32 v[122:123], v[44:45], v[2:3] op_sel_hi:[1,0]
	v_pk_mul_f32 v[120:121], v[84:85], v[120:121]
	v_pk_mul_f32 v[122:123], v[86:87], v[122:123]
	v_cvt_pk_bf16_f32 v90, v120, v121
	v_cvt_pk_bf16_f32 v91, v122, v123
	s_nop 1
	v_permlane32_swap_b32 v88, v90
	v_permlane32_swap_b32 v89, v91
	global_store_dwordx4 v[116:117], v[88:91], off offset:96
	v_pk_mul_f32 v[120:121], v[50:51], v[2:3] op_sel_hi:[1,0]
	v_pk_mul_f32 v[122:123], v[22:23], v[2:3] op_sel_hi:[1,0]
	v_pk_mul_f32 v[120:121], v[80:81], v[120:121]
	v_pk_mul_f32 v[122:123], v[82:83], v[122:123]
	v_cvt_pk_bf16_f32 v80, v120, v121
	v_cvt_pk_bf16_f32 v81, v122, v123
	v_pk_mul_f32 v[120:121], v[198:199], v[2:3] op_sel_hi:[1,0]
	v_pk_mul_f32 v[122:123], v[20:21], v[2:3] op_sel_hi:[1,0]
	v_pk_mul_f32 v[120:121], v[76:77], v[120:121]
	v_pk_mul_f32 v[122:123], v[78:79], v[122:123]
	v_cvt_pk_bf16_f32 v82, v120, v121
	v_cvt_pk_bf16_f32 v83, v122, v123
	s_nop 1
	v_permlane32_swap_b32 v80, v82
	v_permlane32_swap_b32 v81, v83
	global_store_dwordx4 v[116:117], v[80:83], off offset:128
	v_pk_mul_f32 v[120:121], v[202:203], v[2:3] op_sel_hi:[1,0]
	v_pk_mul_f32 v[122:123], v[24:25], v[2:3] op_sel_hi:[1,0]
	v_pk_mul_f32 v[120:121], v[72:73], v[120:121]
	v_pk_mul_f32 v[122:123], v[74:75], v[122:123]
	v_cvt_pk_bf16_f32 v72, v120, v121
	v_cvt_pk_bf16_f32 v73, v122, v123
	v_pk_mul_f32 v[120:121], v[206:207], v[2:3] op_sel_hi:[1,0]
	v_pk_mul_f32 v[122:123], v[34:35], v[2:3] op_sel_hi:[1,0]
	v_pk_mul_f32 v[120:121], v[68:69], v[120:121]
	v_pk_mul_f32 v[122:123], v[70:71], v[122:123]
	v_cvt_pk_bf16_f32 v74, v120, v121
	v_cvt_pk_bf16_f32 v75, v122, v123
	s_nop 1
	v_permlane32_swap_b32 v72, v74
	v_permlane32_swap_b32 v73, v75
	global_store_dwordx4 v[116:117], v[72:75], off offset:160
	v_pk_mul_f32 v[120:121], v[210:211], v[2:3] op_sel_hi:[1,0]
	v_pk_mul_f32 v[122:123], v[208:209], v[2:3] op_sel_hi:[1,0]
	v_pk_mul_f32 v[120:121], v[4:5], v[120:121]
	v_pk_mul_f32 v[122:123], v[6:7], v[122:123]
	v_cvt_pk_bf16_f32 v4, v120, v121
	v_cvt_pk_bf16_f32 v5, v122, v123
	v_pk_mul_f32 v[120:121], v[214:215], v[2:3] op_sel_hi:[1,0]
	v_pk_mul_f32 v[122:123], v[212:213], v[2:3] op_sel_hi:[1,0]
	v_pk_mul_f32 v[120:121], v[8:9], v[120:121]
	v_pk_mul_f32 v[122:123], v[10:11], v[122:123]
	v_cvt_pk_bf16_f32 v6, v120, v121
	v_cvt_pk_bf16_f32 v7, v122, v123
	s_nop 1
	v_permlane32_swap_b32 v4, v6
	v_permlane32_swap_b32 v5, v7
	global_store_dwordx4 v[116:117], v[4:7], off offset:192
	v_pk_mul_f32 v[120:121], v[12:13], v[2:3] op_sel_hi:[1,0]
	v_pk_mul_f32 v[122:123], v[118:119], v[2:3] op_sel_hi:[1,0]
	v_pk_mul_f32 v[120:121], v[26:27], v[120:121]
	v_pk_mul_f32 v[122:123], v[28:29], v[122:123]
	v_cvt_pk_bf16_f32 v8, v120, v121
	v_cvt_pk_bf16_f32 v9, v122, v123
	v_pk_mul_f32 v[120:121], v[14:15], v[2:3] op_sel_hi:[1,0]
	v_pk_mul_f32 v[122:123], v[16:17], v[2:3] op_sel_hi:[1,0]
	v_pk_mul_f32 v[120:121], v[30:31], v[120:121]
	v_pk_mul_f32 v[122:123], v[32:33], v[122:123]
	v_cvt_pk_bf16_f32 v10, v120, v121
	v_cvt_pk_bf16_f32 v11, v122, v123
	s_nop 1
	v_permlane32_swap_b32 v8, v10
	v_permlane32_swap_b32 v9, v11
	global_store_dwordx4 v[116:117], v[8:11], off offset:224

.LBB0_754:
	global_load_dwordx4 v[112:115], v[136:137], off
	global_load_dwordx4 v[108:111], v[136:137], off offset:32
	global_load_dwordx4 v[104:107], v[136:137], off offset:64
	global_load_dwordx4 v[100:103], v[136:137], off offset:96
	global_load_dwordx4 v[96:99], v[136:137], off offset:128
	global_load_dwordx4 v[92:95], v[136:137], off offset:160
	global_load_dwordx4 v[88:91], v[136:137], off offset:192
	global_load_dwordx4 v[84:87], v[136:137], off offset:224
	global_load_dwordx4 v[80:83], v[136:137], off offset:256
	global_load_dwordx4 v[76:79], v[136:137], off offset:288
	global_load_dwordx4 v[72:75], v[136:137], off offset:320
	global_load_dwordx4 v[68:71], v[136:137], off offset:352
	ds_read2st64_b32 v[124:125], v163 offset1:1
	ds_read2st64_b32 v[126:127], v163 offset0:2 offset1:3
	ds_read2st64_b32 v[128:129], v163 offset0:4 offset1:5
	ds_read2st64_b32 v[130:131], v163 offset0:6 offset1:7
	ds_read2st64_b32 v[140:141], v163 offset0:8 offset1:9
	ds_read2st64_b32 v[142:143], v163 offset0:10 offset1:11
	ds_read2st64_b32 v[144:145], v163 offset0:12 offset1:13
	ds_read2st64_b32 v[146:147], v163 offset0:14 offset1:15
	ds_read2st64_b32 v[176:177], v163 offset0:16 offset1:17
	ds_read2st64_b32 v[178:179], v163 offset0:18 offset1:19
	ds_read2st64_b32 v[180:181], v163 offset0:20 offset1:21
	ds_read2st64_b32 v[182:183], v163 offset0:22 offset1:23
	ds_read2st64_b32 v[184:185], v163 offset0:24 offset1:25
	ds_read2st64_b32 v[186:187], v163 offset0:26 offset1:27
	ds_read2st64_b32 v[188:189], v163 offset0:28 offset1:29
	ds_read2st64_b32 v[190:191], v163 offset0:30 offset1:31
	ds_read2st64_b32 v[192:193], v163 offset0:32 offset1:33
	ds_read2st64_b32 v[194:195], v163 offset0:34 offset1:35
	ds_read2st64_b32 v[196:197], v163 offset0:36 offset1:37
	ds_read2st64_b32 v[198:199], v163 offset0:38 offset1:39
	ds_read2st64_b32 v[200:201], v163 offset0:40 offset1:41
	ds_read2st64_b32 v[202:203], v163 offset0:42 offset1:43
	ds_read2st64_b32 v[204:205], v163 offset0:44 offset1:45
	ds_read2st64_b32 v[206:207], v163 offset0:46 offset1:47
	ds_read2st64_b32 v[116:117], v163 offset0:58 offset1:59
	ds_read2st64_b32 v[208:209], v163 offset0:48 offset1:49
	ds_read2st64_b32 v[210:211], v163 offset0:50 offset1:51
	ds_read2st64_b32 v[212:213], v163 offset0:52 offset1:53
	ds_read2st64_b32 v[214:215], v163 offset0:54 offset1:55
	ds_read2st64_b32 v[120:121], v163 offset0:60 offset1:61
	ds_read2st64_b32 v[216:217], v163 offset0:56 offset1:57
	ds_read2st64_b32 v[122:123], v163 offset0:62 offset1:63
	s_waitcnt lgkmcnt(7)
	v_pk_fma_f32 v[116:117], v[14:15], v[2:3], v[116:117] op_sel_hi:[1,0,1] neg_lo:[0,0,1] neg_hi:[0,0,1]
	v_pk_fma_f32 v[64:65], v[64:65], v[2:3], v[144:145] op_sel_hi:[1,0,1] neg_lo:[0,0,1] neg_hi:[0,0,1]
	s_waitcnt lgkmcnt(2)
	v_pk_fma_f32 v[14:15], v[16:17], v[2:3], v[120:121] op_sel_hi:[1,0,1] neg_lo:[0,0,1] neg_hi:[0,0,1]
	v_pk_fma_f32 v[38:39], v[38:39], v[2:3], v[178:179] op_sel_hi:[1,0,1] neg_lo:[0,0,1] neg_hi:[0,0,1]
	s_waitcnt lgkmcnt(0)
	v_pk_fma_f32 v[16:17], v[18:19], v[2:3], v[122:123] op_sel_hi:[1,0,1] neg_lo:[0,0,1] neg_hi:[0,0,1]
	v_pk_fma_f32 v[18:19], v[54:55], v[2:3], v[126:127] op_sel_hi:[1,0,1] neg_lo:[0,0,1] neg_hi:[0,0,1]
	v_pk_fma_f32 v[54:55], v[52:53], v[2:3], v[124:125] op_sel_hi:[1,0,1] neg_lo:[0,0,1] neg_hi:[0,0,1]
	v_pk_mul_f32 v[126:127], v[18:19], v[18:19]
	v_pk_mul_f32 v[124:125], v[54:55], v[54:55]
	v_pk_fma_f32 v[52:53], v[58:59], v[2:3], v[130:131] op_sel_hi:[1,0,1] neg_lo:[0,0,1] neg_hi:[0,0,1]
	v_pk_fma_f32 v[58:59], v[56:57], v[2:3], v[128:129] op_sel_hi:[1,0,1] neg_lo:[0,0,1] neg_hi:[0,0,1]
	v_pk_fma_f32 v[56:57], v[62:63], v[2:3], v[142:143] op_sel_hi:[1,0,1] neg_lo:[0,0,1] neg_hi:[0,0,1]
	v_pk_fma_f32 v[62:63], v[60:61], v[2:3], v[140:141] op_sel_hi:[1,0,1] neg_lo:[0,0,1] neg_hi:[0,0,1]
	v_pk_fma_f32 v[60:61], v[66:67], v[2:3], v[146:147] op_sel_hi:[1,0,1] neg_lo:[0,0,1] neg_hi:[0,0,1]
	v_pk_fma_f32 v[66:67], v[36:37], v[2:3], v[176:177] op_sel_hi:[1,0,1] neg_lo:[0,0,1] neg_hi:[0,0,1]
	v_pk_fma_f32 v[36:37], v[42:43], v[2:3], v[182:183] op_sel_hi:[1,0,1] neg_lo:[0,0,1] neg_hi:[0,0,1]
	v_pk_fma_f32 v[42:43], v[40:41], v[2:3], v[180:181] op_sel_hi:[1,0,1] neg_lo:[0,0,1] neg_hi:[0,0,1]
	v_pk_fma_f32 v[40:41], v[46:47], v[2:3], v[186:187] op_sel_hi:[1,0,1] neg_lo:[0,0,1] neg_hi:[0,0,1]
	v_pk_fma_f32 v[46:47], v[44:45], v[2:3], v[184:185] op_sel_hi:[1,0,1] neg_lo:[0,0,1] neg_hi:[0,0,1]
	v_pk_fma_f32 v[44:45], v[50:51], v[2:3], v[190:191] op_sel_hi:[1,0,1] neg_lo:[0,0,1] neg_hi:[0,0,1]
	v_pk_fma_f32 v[48:49], v[48:49], v[2:3], v[188:189] op_sel_hi:[1,0,1] neg_lo:[0,0,1] neg_hi:[0,0,1]
	v_pk_fma_f32 v[22:23], v[22:23], v[2:3], v[194:195] op_sel_hi:[1,0,1] neg_lo:[0,0,1] neg_hi:[0,0,1]
	v_pk_fma_f32 v[50:51], v[20:21], v[2:3], v[192:193] op_sel_hi:[1,0,1] neg_lo:[0,0,1] neg_hi:[0,0,1]
	v_pk_fma_f32 v[20:21], v[26:27], v[2:3], v[198:199] op_sel_hi:[1,0,1] neg_lo:[0,0,1] neg_hi:[0,0,1]
	v_pk_fma_f32 v[196:197], v[24:25], v[2:3], v[196:197] op_sel_hi:[1,0,1] neg_lo:[0,0,1] neg_hi:[0,0,1]
	v_pk_fma_f32 v[24:25], v[30:31], v[2:3], v[202:203] op_sel_hi:[1,0,1] neg_lo:[0,0,1] neg_hi:[0,0,1]
	v_pk_fma_f32 v[200:201], v[28:29], v[2:3], v[200:201] op_sel_hi:[1,0,1] neg_lo:[0,0,1] neg_hi:[0,0,1]
	v_pk_fma_f32 v[34:35], v[34:35], v[2:3], v[206:207] op_sel_hi:[1,0,1] neg_lo:[0,0,1] neg_hi:[0,0,1]
	v_pk_fma_f32 v[204:205], v[32:33], v[2:3], v[204:205] op_sel_hi:[1,0,1] neg_lo:[0,0,1] neg_hi:[0,0,1]
	v_pk_fma_f32 v[206:207], v[6:7], v[2:3], v[210:211] op_sel_hi:[1,0,1] neg_lo:[0,0,1] neg_hi:[0,0,1]
	v_pk_fma_f32 v[208:209], v[4:5], v[2:3], v[208:209] op_sel_hi:[1,0,1] neg_lo:[0,0,1] neg_hi:[0,0,1]
	v_pk_fma_f32 v[210:211], v[10:11], v[2:3], v[214:215] op_sel_hi:[1,0,1] neg_lo:[0,0,1] neg_hi:[0,0,1]
	v_pk_fma_f32 v[212:213], v[8:9], v[2:3], v[212:213] op_sel_hi:[1,0,1] neg_lo:[0,0,1] neg_hi:[0,0,1]
	v_pk_fma_f32 v[12:13], v[12:13], v[2:3], v[216:217] op_sel_hi:[1,0,1] neg_lo:[0,0,1] neg_hi:[0,0,1]
	v_add_f32_e32 v2, v124, v125
	v_add_f32_e32 v2, v2, v126
	v_pk_mul_f32 v[128:129], v[58:59], v[58:59]
	v_add_f32_e32 v2, v2, v127
	v_add_f32_e32 v2, v2, v128
	v_pk_mul_f32 v[130:131], v[52:53], v[52:53]
	v_add_f32_e32 v2, v2, v129
	v_add_f32_e32 v2, v2, v130
	v_pk_mul_f32 v[140:141], v[62:63], v[62:63]
	v_add_f32_e32 v2, v2, v131
	v_add_f32_e32 v2, v2, v140
	v_pk_mul_f32 v[142:143], v[56:57], v[56:57]
	v_add_f32_e32 v2, v2, v141
	v_add_f32_e32 v2, v2, v142
	v_pk_mul_f32 v[144:145], v[64:65], v[64:65]
	v_add_f32_e32 v2, v2, v143
	v_add_f32_e32 v2, v2, v144
	v_pk_mul_f32 v[146:147], v[60:61], v[60:61]
	v_add_f32_e32 v2, v2, v145
	v_add_f32_e32 v2, v2, v146
	v_pk_mul_f32 v[176:177], v[66:67], v[66:67]
	v_add_f32_e32 v2, v2, v147
	v_add_f32_e32 v2, v2, v176
	v_pk_mul_f32 v[178:179], v[38:39], v[38:39]
	v_add_f32_e32 v2, v2, v177
	v_add_f32_e32 v2, v2, v178
	v_pk_mul_f32 v[180:181], v[42:43], v[42:43]
	v_add_f32_e32 v2, v2, v179
	v_add_f32_e32 v2, v2, v180
	v_pk_mul_f32 v[182:183], v[36:37], v[36:37]
	v_add_f32_e32 v2, v2, v181
	v_add_f32_e32 v2, v2, v182
	v_pk_mul_f32 v[184:185], v[46:47], v[46:47]
	v_add_f32_e32 v2, v2, v183
	v_add_f32_e32 v2, v2, v184
	v_pk_mul_f32 v[186:187], v[40:41], v[40:41]
	v_add_f32_e32 v2, v2, v185
	v_add_f32_e32 v2, v2, v186
	v_pk_mul_f32 v[188:189], v[48:49], v[48:49]
	v_add_f32_e32 v2, v2, v187
	v_add_f32_e32 v2, v2, v188
	v_pk_mul_f32 v[190:191], v[44:45], v[44:45]
	v_add_f32_e32 v2, v2, v189
	v_add_f32_e32 v2, v2, v190
	v_pk_mul_f32 v[192:193], v[50:51], v[50:51]
	v_add_f32_e32 v2, v2, v191
	v_add_f32_e32 v2, v2, v192
	v_pk_mul_f32 v[194:195], v[22:23], v[22:23]
	v_add_f32_e32 v2, v2, v193
	v_add_f32_e32 v2, v2, v194
	v_pk_mul_f32 v[198:199], v[196:197], v[196:197]
	v_add_f32_e32 v2, v2, v195
	v_add_f32_e32 v2, v2, v198
	v_pk_mul_f32 v[26:27], v[20:21], v[20:21]
	v_add_f32_e32 v2, v2, v199
	v_add_f32_e32 v2, v2, v26
	v_pk_mul_f32 v[28:29], v[200:201], v[200:201]
	v_add_f32_e32 v2, v2, v27
	v_add_f32_e32 v2, v2, v28
	v_pk_mul_f32 v[30:31], v[24:25], v[24:25]
	v_add_f32_e32 v2, v2, v29
	v_add_f32_e32 v2, v2, v30
	v_pk_mul_f32 v[32:33], v[204:205], v[204:205]
	v_add_f32_e32 v2, v2, v31
	v_add_f32_e32 v2, v2, v32
	v_pk_mul_f32 v[202:203], v[34:35], v[34:35]
	v_add_f32_e32 v2, v2, v33
	v_add_f32_e32 v2, v2, v202
	v_pk_mul_f32 v[4:5], v[208:209], v[208:209]
	v_add_f32_e32 v2, v2, v203
	v_add_f32_e32 v2, v2, v4
	v_pk_mul_f32 v[6:7], v[206:207], v[206:207]
	v_add_f32_e32 v2, v2, v5
	v_add_f32_e32 v2, v2, v6
	v_pk_mul_f32 v[8:9], v[212:213], v[212:213]
	v_add_f32_e32 v2, v2, v7
	v_add_f32_e32 v2, v2, v8
	v_pk_mul_f32 v[10:11], v[210:211], v[210:211]
	v_add_f32_e32 v2, v2, v9
	v_add_f32_e32 v2, v2, v10
	v_pk_mul_f32 v[214:215], v[12:13], v[12:13]
	v_add_f32_e32 v2, v2, v11
	v_add_f32_e32 v2, v2, v214
	v_pk_mul_f32 v[118:119], v[116:117], v[116:117]
	v_add_f32_e32 v2, v2, v215
	v_add_f32_e32 v2, v2, v118
	global_load_dwordx4 v[4:7], v[136:137], off offset:384
	global_load_dwordx4 v[8:11], v[136:137], off offset:416
	global_load_dwordx4 v[26:29], v[136:137], off offset:448
	global_load_dwordx4 v[30:33], v[136:137], off offset:480
	v_pk_mul_f32 v[120:121], v[14:15], v[14:15]
	v_add_f32_e32 v2, v2, v119
	v_add_f32_e32 v2, v2, v120
	v_pk_mul_f32 v[122:123], v[16:17], v[16:17]
	v_add_f32_e32 v2, v2, v121
	v_add_f32_e32 v2, v2, v122
	v_add_f32_e32 v2, v2, v123
	ds_bpermute_b32 v118, v1, v2
	s_lshl_b32 s6, s69, 1
	s_waitcnt lgkmcnt(0)
	v_add_f32_e32 v2, v2, v118
	v_fmamk_f32 v2, v2, 0x3c000000, v173
	v_mul_f32_e32 v118, 0x4f800000, v2
	v_cmp_gt_f32_e32 vcc, s66, v2
	s_nop 1
	v_cndmask_b32_e32 v2, v2, v118, vcc
	v_sqrt_f32_e32 v120, v2
	v_lshlrev_b64 v[118:119], 11, v[138:139]
	v_lshl_add_u64 v[118:119], s[4:5], 0, v[118:119]
	v_lshl_add_u64 v[118:119], v[118:119], 0, s[6:7]
	v_add_u32_e32 v121, -1, v120
	v_fma_f32 v122, -v121, v120, v2
	v_cmp_ge_f32_e64 s[0:1], 0, v122
	v_add_u32_e32 v122, 1, v120
	s_nop 0
	v_cndmask_b32_e64 v121, v120, v121, s[0:1]
	v_fma_f32 v120, -v122, v120, v2
	v_cmp_lt_f32_e64 s[0:1], 0, v120
	s_nop 1
	v_cndmask_b32_e64 v120, v121, v122, s[0:1]
	v_mul_f32_e32 v121, 0x37800000, v120
	v_cndmask_b32_e32 v120, v120, v121, vcc
	v_cmp_class_f32_e32 vcc, v2, v174
	s_nop 1
	v_cndmask_b32_e32 v120, v120, v2, vcc
	v_div_scale_f32 v121, s[0:1], v120, v120, s67
	v_rcp_f32_e32 v122, v121
	v_lshlrev_b32_e32 v2, 1, v134
	v_lshl_add_u64 v[118:119], v[118:119], 0, v[2:3]
	v_fma_f32 v2, -v121, v122, 1.0
	v_fmac_f32_e32 v122, v2, v122
	v_div_scale_f32 v2, vcc, s67, v120, s67
	v_mul_f32_e32 v123, v2, v122
	v_fma_f32 v124, -v121, v123, v2
	v_fmac_f32_e32 v123, v124, v122
	v_fma_f32 v2, -v121, v123, v2
	v_div_fmas_f32 v2, v2, v122, v123
	v_div_fixup_f32 v2, v2, v120, s67
	s_waitcnt vmcnt(0)
	v_mbcnt_lo_u32_b32 v124, -1, 0
	v_mbcnt_hi_u32_b32 v124, -1, v124
	v_and_b32_e32 v124, 32, v124
	v_lshrrev_b32_e32 v124, 2, v124
	v_mov_b32_e32 v125, 0
	v_lshl_add_u64 v[118:119], v[118:119], 0, v[124:125]
	v_pk_mul_f32 v[120:121], v[54:55], v[2:3] op_sel_hi:[1,0]
	v_pk_mul_f32 v[122:123], v[18:19], v[2:3] op_sel_hi:[1,0]
	v_pk_mul_f32 v[120:121], v[112:113], v[120:121]
	v_pk_mul_f32 v[122:123], v[114:115], v[122:123]
	v_cvt_pk_bf16_f32 v112, v120, v121
	v_cvt_pk_bf16_f32 v113, v122, v123
	v_pk_mul_f32 v[120:121], v[58:59], v[2:3] op_sel_hi:[1,0]
	v_pk_mul_f32 v[122:123], v[52:53], v[2:3] op_sel_hi:[1,0]
	v_pk_mul_f32 v[120:121], v[108:109], v[120:121]
	v_pk_mul_f32 v[122:123], v[110:111], v[122:123]
	v_cvt_pk_bf16_f32 v114, v120, v121
	v_cvt_pk_bf16_f32 v115, v122, v123
	s_nop 1
	v_permlane32_swap_b32 v112, v114
	v_permlane32_swap_b32 v113, v115
	global_store_dwordx4 v[118:119], v[112:115], off
	v_pk_mul_f32 v[120:121], v[62:63], v[2:3] op_sel_hi:[1,0]
	v_pk_mul_f32 v[122:123], v[56:57], v[2:3] op_sel_hi:[1,0]
	v_pk_mul_f32 v[120:121], v[104:105], v[120:121]
	v_pk_mul_f32 v[122:123], v[106:107], v[122:123]
	v_cvt_pk_bf16_f32 v104, v120, v121
	v_cvt_pk_bf16_f32 v105, v122, v123
	v_pk_mul_f32 v[120:121], v[64:65], v[2:3] op_sel_hi:[1,0]
	v_pk_mul_f32 v[122:123], v[60:61], v[2:3] op_sel_hi:[1,0]
	v_pk_mul_f32 v[120:121], v[100:101], v[120:121]
	v_pk_mul_f32 v[122:123], v[102:103], v[122:123]
	v_cvt_pk_bf16_f32 v106, v120, v121
	v_cvt_pk_bf16_f32 v107, v122, v123
	s_nop 1
	v_permlane32_swap_b32 v104, v106
	v_permlane32_swap_b32 v105, v107
	global_store_dwordx4 v[118:119], v[104:107], off offset:32
	v_pk_mul_f32 v[120:121], v[66:67], v[2:3] op_sel_hi:[1,0]
	v_pk_mul_f32 v[122:123], v[38:39], v[2:3] op_sel_hi:[1,0]
	v_pk_mul_f32 v[120:121], v[96:97], v[120:121]
	v_pk_mul_f32 v[122:123], v[98:99], v[122:123]
	v_cvt_pk_bf16_f32 v96, v120, v121
	v_cvt_pk_bf16_f32 v97, v122, v123
	v_pk_mul_f32 v[120:121], v[42:43], v[2:3] op_sel_hi:[1,0]
	v_pk_mul_f32 v[122:123], v[36:37], v[2:3] op_sel_hi:[1,0]
	v_pk_mul_f32 v[120:121], v[92:93], v[120:121]
	v_pk_mul_f32 v[122:123], v[94:95], v[122:123]
	v_cvt_pk_bf16_f32 v98, v120, v121
	v_cvt_pk_bf16_f32 v99, v122, v123
	s_nop 1
	v_permlane32_swap_b32 v96, v98
	v_permlane32_swap_b32 v97, v99
	global_store_dwordx4 v[118:119], v[96:99], off offset:64
	v_pk_mul_f32 v[120:121], v[46:47], v[2:3] op_sel_hi:[1,0]
	v_pk_mul_f32 v[122:123], v[40:41], v[2:3] op_sel_hi:[1,0]
	v_pk_mul_f32 v[120:121], v[88:89], v[120:121]
	v_pk_mul_f32 v[122:123], v[90:91], v[122:123]
	v_cvt_pk_bf16_f32 v88, v120, v121
	v_cvt_pk_bf16_f32 v89, v122, v123
	v_pk_mul_f32 v[120:121], v[48:49], v[2:3] op_sel_hi:[1,0]
	v_pk_mul_f32 v[122:123], v[44:45], v[2:3] op_sel_hi:[1,0]
	v_pk_mul_f32 v[120:121], v[84:85], v[120:121]
	v_pk_mul_f32 v[122:123], v[86:87], v[122:123]
	v_cvt_pk_bf16_f32 v90, v120, v121
	v_cvt_pk_bf16_f32 v91, v122, v123
	s_nop 1
	v_permlane32_swap_b32 v88, v90
	v_permlane32_swap_b32 v89, v91
	global_store_dwordx4 v[118:119], v[88:91], off offset:96
	v_pk_mul_f32 v[120:121], v[50:51], v[2:3] op_sel_hi:[1,0]
	v_pk_mul_f32 v[122:123], v[22:23], v[2:3] op_sel_hi:[1,0]
	v_pk_mul_f32 v[120:121], v[80:81], v[120:121]
	v_pk_mul_f32 v[122:123], v[82:83], v[122:123]
	v_cvt_pk_bf16_f32 v80, v120, v121
	v_cvt_pk_bf16_f32 v81, v122, v123
	v_pk_mul_f32 v[120:121], v[196:197], v[2:3] op_sel_hi:[1,0]
	v_pk_mul_f32 v[122:123], v[20:21], v[2:3] op_sel_hi:[1,0]
	v_pk_mul_f32 v[120:121], v[76:77], v[120:121]
	v_pk_mul_f32 v[122:123], v[78:79], v[122:123]
	v_cvt_pk_bf16_f32 v82, v120, v121
	v_cvt_pk_bf16_f32 v83, v122, v123
	s_nop 1
	v_permlane32_swap_b32 v80, v82
	v_permlane32_swap_b32 v81, v83
	global_store_dwordx4 v[118:119], v[80:83], off offset:128
	v_pk_mul_f32 v[120:121], v[200:201], v[2:3] op_sel_hi:[1,0]
	v_pk_mul_f32 v[122:123], v[24:25], v[2:3] op_sel_hi:[1,0]
	v_pk_mul_f32 v[120:121], v[72:73], v[120:121]
	v_pk_mul_f32 v[122:123], v[74:75], v[122:123]
	v_cvt_pk_bf16_f32 v72, v120, v121
	v_cvt_pk_bf16_f32 v73, v122, v123
	v_pk_mul_f32 v[120:121], v[204:205], v[2:3] op_sel_hi:[1,0]
	v_pk_mul_f32 v[122:123], v[34:35], v[2:3] op_sel_hi:[1,0]
	v_pk_mul_f32 v[120:121], v[68:69], v[120:121]
	v_pk_mul_f32 v[122:123], v[70:71], v[122:123]
	v_cvt_pk_bf16_f32 v74, v120, v121
	v_cvt_pk_bf16_f32 v75, v122, v123
	s_nop 1
	v_permlane32_swap_b32 v72, v74
	v_permlane32_swap_b32 v73, v75
	global_store_dwordx4 v[118:119], v[72:75], off offset:160
	v_pk_mul_f32 v[120:121], v[208:209], v[2:3] op_sel_hi:[1,0]
	v_pk_mul_f32 v[122:123], v[206:207], v[2:3] op_sel_hi:[1,0]
	v_pk_mul_f32 v[120:121], v[4:5], v[120:121]
	v_pk_mul_f32 v[122:123], v[6:7], v[122:123]
	v_cvt_pk_bf16_f32 v4, v120, v121
	v_cvt_pk_bf16_f32 v5, v122, v123
	v_pk_mul_f32 v[120:121], v[212:213], v[2:3] op_sel_hi:[1,0]
	v_pk_mul_f32 v[122:123], v[210:211], v[2:3] op_sel_hi:[1,0]
	v_pk_mul_f32 v[120:121], v[8:9], v[120:121]
	v_pk_mul_f32 v[122:123], v[10:11], v[122:123]
	v_cvt_pk_bf16_f32 v6, v120, v121
	v_cvt_pk_bf16_f32 v7, v122, v123
	s_nop 1
	v_permlane32_swap_b32 v4, v6
	v_permlane32_swap_b32 v5, v7
	global_store_dwordx4 v[118:119], v[4:7], off offset:192
	v_pk_mul_f32 v[120:121], v[12:13], v[2:3] op_sel_hi:[1,0]
	v_pk_mul_f32 v[122:123], v[116:117], v[2:3] op_sel_hi:[1,0]
	v_pk_mul_f32 v[120:121], v[26:27], v[120:121]
	v_pk_mul_f32 v[122:123], v[28:29], v[122:123]
	v_cvt_pk_bf16_f32 v8, v120, v121
	v_cvt_pk_bf16_f32 v9, v122, v123
	v_pk_mul_f32 v[120:121], v[14:15], v[2:3] op_sel_hi:[1,0]
	v_pk_mul_f32 v[122:123], v[16:17], v[2:3] op_sel_hi:[1,0]
	v_pk_mul_f32 v[120:121], v[30:31], v[120:121]
	v_pk_mul_f32 v[122:123], v[32:33], v[122:123]
	v_cvt_pk_bf16_f32 v10, v120, v121
	v_cvt_pk_bf16_f32 v11, v122, v123
	s_nop 1
	v_permlane32_swap_b32 v8, v10
	v_permlane32_swap_b32 v9, v11
	global_store_dwordx4 v[118:119], v[8:11], off offset:224
	s_branch .LBB0_721
